# cooperative NSA selected branch: cross-half max via v_permlane32_swap instead of the second ds_bpermute round trip
# speedup vs baseline: 1.0098x; 1.0098x over previous
; DI bf16_t f2bf(float f) { unsigned u = __float_as_uint(f); u += 0x7fffu + ((u >> 16) & 1u); return (bf16_t)(u >> 16); }
; DI float fexp(float x) { return __builtin_amdgcn_exp2f(x * 1.4426950408889634f); }
; #define MFMA16(a, b, c) __builtin_amdgcn_mfma_f32_16x16x32_bf16((a), (b), (c), 0, 0, 0)
; DI void sel_compute(const SelRegs& rg, const bf16x8 (&qf)[2], int kb0, bool colsel, int stk, int quad, float& m, float& lsum, f32x4 (&Os)[4]) {
;   f32x4 sa = {0.f, 0.f, 0.f, 0.f}, sb = {0.f, 0.f, 0.f, 0.f};
; #pragma unroll
;   for (int ks = 0; ks < 2; ++ks) { sa = MFMA16(__builtin_bit_cast(bf16x8, rg.ka[ks]), qf[ks], sa); sb = MFMA16(__builtin_bit_cast(bf16x8, rg.kb[ks]), qf[ks], sb); }
;   float mx = m;
; #pragma unroll
;   for (int i = 0; i < 4; ++i) { const int ka = kb0 + 8 * quad + i;
;     const float va = (colsel && ka <= stk) ? sa[i] * 0.125f : -1e30f, vb = (colsel && ka + 4 <= stk) ? sb[i] * 0.125f : -1e30f;
;     sa[i] = va; sb[i] = vb; mx = fmaxf(mx, fmaxf(va, vb)); }
;   mx = fmaxf(mx, __shfl_xor(mx, 16)); mx = fmaxf(mx, __shfl_xor(mx, 32));
;   const float corr = fexp(m - mx); m = mx; float ps = 0.f;
; #pragma unroll
;   for (int i = 0; i < 4; ++i) { const float pa = sa[i] > -1e29f ? fexp(sa[i] - mx) : 0.f, pb = sb[i] > -1e29f ? fexp(sb[i] - mx) : 0.f; sa[i] = pa; sb[i] = pb; ps += pa + pb; }
;   lsum = lsum * corr + ps;
;   bf16x8 pf;
; #pragma unroll
;   for (int i = 0; i < 4; ++i) { pf[i] = (short)f2bf(sa[i]); pf[4 + i] = (short)f2bf(sb[i]); }
; #pragma unroll
;   for (int dt = 0; dt < 4; ++dt) { Os[dt][0] *= corr; Os[dt][1] *= corr; Os[dt][2] *= corr; Os[dt][3] *= corr; Os[dt] = MFMA16(__builtin_bit_cast(bf16x8, rg.v[dt]), pf, Os[dt]); }
; }
.Lsc_noload:
	s_and_b32 s1, s5, 63
	v_readlane_b32 s0, v88, s1
	v_readlane_b32 s2, v89, s1
	s_cmp_lt_u32 s5, 64
	s_cselect_b32 s0, s0, s2
	s_lshr_b32 s0, s0, s4
	s_and_b32 s9, s0, 15
	s_cmp_eq_u32 s9, 0
	s_cbranch_scc1 .Lsc_skip
	v_add_u32_e32 v97, s7, v95
	v_add_u32_e32 v98, s7, v96
	ds_read_b128 v[40:43], v97 offset:20480
	ds_read_b128 v[44:47], v97 offset:21056
	ds_read_b128 v[48:51], v97 offset:20544
	ds_read_b128 v[52:55], v97 offset:21120
	ds_read_b128 v[56:59], v98 offset:29696
	ds_read_b128 v[60:63], v98 offset:32000
	ds_read_b128 v[64:67], v98 offset:34304
	ds_read_b128 v[68:71], v98 offset:36608
	s_lshl_b32 s12, s5, 6
	s_waitcnt lgkmcnt(4)
	v_mfma_f32_16x16x32_bf16 v[150:153], v[40:43], v[4:7], 0
	v_mfma_f32_16x16x32_bf16 v[154:157], v[44:47], v[4:7], 0
	v_mfma_f32_16x16x32_bf16 v[150:153], v[48:51], v[8:11], v[150:153]
	v_mfma_f32_16x16x32_bf16 v[154:157], v[52:55], v[8:11], v[154:157]
	v_and_b32_e32 v134, s9, v238
	v_cmp_ne_u32_e32 vcc, 0, v134
	v_subrev_u32_e32 v129, s12, v236
	s_nop 1
	v_cndmask_b32_e32 v134, -1, v129, vcc
	v_cmp_le_i32_e64 s[40:41], 0, v134
	v_cmp_le_i32_e64 s[42:43], 1, v134
	v_cmp_le_i32_e64 s[44:45], 2, v134
	v_cmp_le_i32_e64 s[46:47], 3, v134
	v_cndmask_b32_e64 v158, v240, 0, s[40:41]
	v_cndmask_b32_e64 v159, v240, 0, s[42:43]
	v_cndmask_b32_e64 v160, v240, 0, s[44:45]
	v_cndmask_b32_e64 v161, v240, 0, s[46:47]
	v_cmp_le_i32_e64 s[40:41], 4, v134
	v_cmp_le_i32_e64 s[42:43], 5, v134
	v_cmp_le_i32_e64 s[44:45], 6, v134
	v_cmp_le_i32_e64 s[46:47], 7, v134
	v_cndmask_b32_e64 v162, v240, 0, s[40:41]
	v_cndmask_b32_e64 v163, v240, 0, s[42:43]
	v_cndmask_b32_e64 v164, v240, 0, s[44:45]
	v_cndmask_b32_e64 v165, v240, 0, s[46:47]
	v_fma_f32 v150, v150, s6, v158
	v_fma_f32 v151, v151, s6, v159
	v_fma_f32 v152, v152, s6, v160
	v_fma_f32 v153, v153, s6, v161
	v_fma_f32 v154, v154, s6, v162
	v_fma_f32 v155, v155, s6, v163
	v_fma_f32 v156, v156, s6, v164
	v_fma_f32 v157, v157, s6, v165
	v_max3_f32 v128, v150, v151, v152
	v_max3_f32 v129, v153, v154, v155
	v_max3_f32 v133, v156, v157, v132
	v_max3_f32 v128, v128, v129, v133
	ds_bpermute_b32 v129, v125, v128
	s_waitcnt lgkmcnt(0)
	v_max_f32_e32 v128, v128, v129
	v_mov_b32_e32 v129, v128
	v_mov_b32_e32 v133, v128
	s_nop 1
	v_permlane32_swap_b32_e32 v129, v133
	v_max_f32_e32 v128, v129, v133
	v_sub_f32_e32 v130, v132, v128
	v_exp_f32_e32 v130, v130
	v_mov_b32_e32 v132, v128
	v_sub_f32_e32 v150, v150, v128
	v_sub_f32_e32 v151, v151, v128
	v_sub_f32_e32 v152, v152, v128
	v_sub_f32_e32 v153, v153, v128
	v_sub_f32_e32 v154, v154, v128
	v_sub_f32_e32 v155, v155, v128
	v_sub_f32_e32 v156, v156, v128
	v_sub_f32_e32 v157, v157, v128
	v_exp_f32_e32 v150, v150
	v_exp_f32_e32 v151, v151
	v_exp_f32_e32 v152, v152
	v_exp_f32_e32 v153, v153
	v_exp_f32_e32 v154, v154
	v_exp_f32_e32 v155, v155
	v_exp_f32_e32 v156, v156
	v_exp_f32_e32 v157, v157
	v_pk_mul_f32 v[36:37], v[36:37], v[130:131] op_sel_hi:[1,0]
	v_pk_mul_f32 v[38:39], v[38:39], v[130:131] op_sel_hi:[1,0]
	v_pk_mul_f32 v[32:33], v[32:33], v[130:131] op_sel_hi:[1,0]
	v_pk_mul_f32 v[34:35], v[34:35], v[130:131] op_sel_hi:[1,0]
	v_pk_mul_f32 v[28:29], v[28:29], v[130:131] op_sel_hi:[1,0]
	v_pk_mul_f32 v[30:31], v[30:31], v[130:131] op_sel_hi:[1,0]
	v_pk_mul_f32 v[24:25], v[24:25], v[130:131] op_sel_hi:[1,0]
	v_pk_mul_f32 v[26:27], v[26:27], v[130:131] op_sel_hi:[1,0]
	v_add_f32_e32 v129, v150, v151
	v_add_f32_e32 v133, v152, v153
	v_add_f32_e32 v129, v129, v154
	v_add_f32_e32 v133, v133, v155
	v_add_f32_e32 v129, v129, v156
	v_add_f32_e32 v133, v133, v157
	v_add_f32_e32 v129, v129, v133
	v_fma_f32 v131, v131, v130, v129
	v_cvt_pk_bf16_f32 v166, v150, v151
	v_cvt_pk_bf16_f32 v167, v152, v153
	v_cvt_pk_bf16_f32 v168, v154, v155
	v_cvt_pk_bf16_f32 v169, v156, v157
	s_nop 1
	v_mfma_f32_16x16x32_bf16 v[36:39], v[56:59], v[166:169], v[36:39]
	v_mfma_f32_16x16x32_bf16 v[32:35], v[60:63], v[166:169], v[32:35]
	v_mfma_f32_16x16x32_bf16 v[28:31], v[64:67], v[166:169], v[28:31]
	v_mfma_f32_16x16x32_bf16 v[24:27], v[68:71], v[166:169], v[24:27]
	ds_read_b128 v[40:43], v97 offset:25088
	ds_read_b128 v[44:47], v97 offset:25664
	ds_read_b128 v[48:51], v97 offset:25152
	ds_read_b128 v[52:55], v97 offset:25728
	ds_read_b128 v[56:59], v98 offset:29760
	ds_read_b128 v[60:63], v98 offset:32064
	ds_read_b128 v[64:67], v98 offset:34368
	ds_read_b128 v[68:71], v98 offset:36672
	s_lshl_b32 s12, s5, 6
	s_add_i32 s12, s12, 32
	s_waitcnt lgkmcnt(4)
; DI bf16_t f2bf(float f) { unsigned u = __float_as_uint(f); u += 0x7fffu + ((u >> 16) & 1u); return (bf16_t)(u >> 16); }
; DI float fexp(float x) { return __builtin_amdgcn_exp2f(x * 1.4426950408889634f); }
; #define MFMA16(a, b, c) __builtin_amdgcn_mfma_f32_16x16x32_bf16((a), (b), (c), 0, 0, 0)
; DI void sel_compute(const SelRegs& rg, const bf16x8 (&qf)[2], int kb0, bool colsel, int stk, int quad, float& m, float& lsum, f32x4 (&Os)[4]) {
;   f32x4 sa = {0.f, 0.f, 0.f, 0.f}, sb = {0.f, 0.f, 0.f, 0.f};
; #pragma unroll
;   for (int ks = 0; ks < 2; ++ks) { sa = MFMA16(__builtin_bit_cast(bf16x8, rg.ka[ks]), qf[ks], sa); sb = MFMA16(__builtin_bit_cast(bf16x8, rg.kb[ks]), qf[ks], sb); }
;   float mx = m;
; #pragma unroll
;   for (int i = 0; i < 4; ++i) { const int ka = kb0 + 8 * quad + i;
;     const float va = (colsel && ka <= stk) ? sa[i] * 0.125f : -1e30f, vb = (colsel && ka + 4 <= stk) ? sb[i] * 0.125f : -1e30f;
;     sa[i] = va; sb[i] = vb; mx = fmaxf(mx, fmaxf(va, vb)); }
;   mx = fmaxf(mx, __shfl_xor(mx, 16)); mx = fmaxf(mx, __shfl_xor(mx, 32));
;   const float corr = fexp(m - mx); m = mx; float ps = 0.f;
; #pragma unroll
;   for (int i = 0; i < 4; ++i) { const float pa = sa[i] > -1e29f ? fexp(sa[i] - mx) : 0.f, pb = sb[i] > -1e29f ? fexp(sb[i] - mx) : 0.f; sa[i] = pa; sb[i] = pb; ps += pa + pb; }
;   lsum = lsum * corr + ps;
;   bf16x8 pf;
; #pragma unroll
;   for (int i = 0; i < 4; ++i) { pf[i] = (short)f2bf(sa[i]); pf[4 + i] = (short)f2bf(sb[i]); }
; #pragma unroll
;   for (int dt = 0; dt < 4; ++dt) { Os[dt][0] *= corr; Os[dt][1] *= corr; Os[dt][2] *= corr; Os[dt][3] *= corr; Os[dt] = MFMA16(__builtin_bit_cast(bf16x8, rg.v[dt]), pf, Os[dt]); }
; }
	v_mfma_f32_16x16x32_bf16 v[150:153], v[40:43], v[4:7], 0
	v_mfma_f32_16x16x32_bf16 v[154:157], v[44:47], v[4:7], 0
	v_mfma_f32_16x16x32_bf16 v[150:153], v[48:51], v[8:11], v[150:153]
	v_mfma_f32_16x16x32_bf16 v[154:157], v[52:55], v[8:11], v[154:157]
	v_and_b32_e32 v134, s9, v238
	v_cmp_ne_u32_e32 vcc, 0, v134
	v_subrev_u32_e32 v129, s12, v236
	s_nop 1
	v_cndmask_b32_e32 v134, -1, v129, vcc
	v_cmp_le_i32_e64 s[40:41], 0, v134
	v_cmp_le_i32_e64 s[42:43], 1, v134
	v_cmp_le_i32_e64 s[44:45], 2, v134
	v_cmp_le_i32_e64 s[46:47], 3, v134
	v_cndmask_b32_e64 v158, v240, 0, s[40:41]
	v_cndmask_b32_e64 v159, v240, 0, s[42:43]
	v_cndmask_b32_e64 v160, v240, 0, s[44:45]
	v_cndmask_b32_e64 v161, v240, 0, s[46:47]
	v_cmp_le_i32_e64 s[40:41], 4, v134
	v_cmp_le_i32_e64 s[42:43], 5, v134
	v_cmp_le_i32_e64 s[44:45], 6, v134
	v_cmp_le_i32_e64 s[46:47], 7, v134
	v_cndmask_b32_e64 v162, v240, 0, s[40:41]
	v_cndmask_b32_e64 v163, v240, 0, s[42:43]
	v_cndmask_b32_e64 v164, v240, 0, s[44:45]
	v_cndmask_b32_e64 v165, v240, 0, s[46:47]
	v_fma_f32 v150, v150, s6, v158
	v_fma_f32 v151, v151, s6, v159
	v_fma_f32 v152, v152, s6, v160
	v_fma_f32 v153, v153, s6, v161
	v_fma_f32 v154, v154, s6, v162
	v_fma_f32 v155, v155, s6, v163
	v_fma_f32 v156, v156, s6, v164
	v_fma_f32 v157, v157, s6, v165
	v_max3_f32 v128, v150, v151, v152
	v_max3_f32 v129, v153, v154, v155
	v_max3_f32 v133, v156, v157, v132
	v_max3_f32 v128, v128, v129, v133
	ds_bpermute_b32 v129, v125, v128
	s_waitcnt lgkmcnt(0)
	v_max_f32_e32 v128, v128, v129
	v_mov_b32_e32 v129, v128
	v_mov_b32_e32 v133, v128
	s_nop 1
	v_permlane32_swap_b32_e32 v129, v133
	v_max_f32_e32 v128, v129, v133
	v_sub_f32_e32 v130, v132, v128
	v_exp_f32_e32 v130, v130
	v_mov_b32_e32 v132, v128
	v_sub_f32_e32 v150, v150, v128
	v_sub_f32_e32 v151, v151, v128
	v_sub_f32_e32 v152, v152, v128
	v_sub_f32_e32 v153, v153, v128
	v_sub_f32_e32 v154, v154, v128
	v_sub_f32_e32 v155, v155, v128
	v_sub_f32_e32 v156, v156, v128
	v_sub_f32_e32 v157, v157, v128
	v_exp_f32_e32 v150, v150
	v_exp_f32_e32 v151, v151
	v_exp_f32_e32 v152, v152
	v_exp_f32_e32 v153, v153
	v_exp_f32_e32 v154, v154
	v_exp_f32_e32 v155, v155
	v_exp_f32_e32 v156, v156
	v_exp_f32_e32 v157, v157
	v_pk_mul_f32 v[36:37], v[36:37], v[130:131] op_sel_hi:[1,0]
	v_pk_mul_f32 v[38:39], v[38:39], v[130:131] op_sel_hi:[1,0]
	v_pk_mul_f32 v[32:33], v[32:33], v[130:131] op_sel_hi:[1,0]
	v_pk_mul_f32 v[34:35], v[34:35], v[130:131] op_sel_hi:[1,0]
	v_pk_mul_f32 v[28:29], v[28:29], v[130:131] op_sel_hi:[1,0]
	v_pk_mul_f32 v[30:31], v[30:31], v[130:131] op_sel_hi:[1,0]
	v_pk_mul_f32 v[24:25], v[24:25], v[130:131] op_sel_hi:[1,0]
	v_pk_mul_f32 v[26:27], v[26:27], v[130:131] op_sel_hi:[1,0]
	v_add_f32_e32 v129, v150, v151
	v_add_f32_e32 v133, v152, v153
	v_add_f32_e32 v129, v129, v154
	v_add_f32_e32 v133, v133, v155
	v_add_f32_e32 v129, v129, v156
	v_add_f32_e32 v133, v133, v157
	v_add_f32_e32 v129, v129, v133
	v_fma_f32 v131, v131, v130, v129
	v_cvt_pk_bf16_f32 v166, v150, v151
	v_cvt_pk_bf16_f32 v167, v152, v153
	v_cvt_pk_bf16_f32 v168, v154, v155
	v_cvt_pk_bf16_f32 v169, v156, v157
	s_nop 1
	v_mfma_f32_16x16x32_bf16 v[36:39], v[56:59], v[166:169], v[36:39]
	v_mfma_f32_16x16x32_bf16 v[32:35], v[60:63], v[166:169], v[32:35]
	v_mfma_f32_16x16x32_bf16 v[28:31], v[64:67], v[166:169], v[28:31]
	v_mfma_f32_16x16x32_bf16 v[24:27], v[68:71], v[166:169], v[24:27]
